# MLA bodies: running-reference (non-fixed) blocks moved out of line so the fixed-reference path falls through
# speedup vs baseline: 1.0213x; 1.0213x over previous
.LBB0_1193:
	s_mov_b64 s[14:15], 0x3600180
	s_add_i32 s17, s16, 0x12000
	v_lshl_add_u64 v[80:81], v[188:189], 0, s[14:15]
	s_add_i32 m0, s17, s66
	v_exp_f32_e32 v150, v64
	global_load_lds_dwordx4 v[80:81], off
	ds_read_b128 v[80:83], v199 offset:12288
	ds_read_b128 v[84:87], v199 offset:18432
	ds_read_b128 v[154:157], v200 offset:12288
	ds_read_b128 v[202:205], v200 offset:18432
	ds_read_b128 v[212:215], v199 offset:12352
	ds_read_b128 v[220:223], v199 offset:18496
	ds_read_b128 v[224:227], v200 offset:12352
	ds_read_b128 v[228:231], v200 offset:18496
	ds_read_b128 v[232:235], v199 offset:12416
	ds_read_b128 v[236:239], v199 offset:18560
	ds_read_b128 v[240:243], v200 offset:12416
	ds_read_b128 v[244:247], v200 offset:18560
	s_waitcnt lgkmcnt(0)
	v_mfma_f32_32x32x16_bf16 v[96:111], v[80:83], v[136:139], 0
	v_exp_f32_e32 v151, v65
	v_exp_f32_e32 v152, v48
	v_exp_f32_e32 v153, v49
	v_exp_f32_e32 v167, v50
	v_exp_f32_e32 v169, v51
	v_exp_f32_e32 v201, v69
	v_exp_f32_e32 v208, v52
	v_mfma_f32_32x32x16_bf16 v[80:95], v[84:87], v[136:139], 0
	v_exp_f32_e32 v209, v55
	v_exp_f32_e32 v219, v74
	v_mfma_f32_32x32x16_bf16 v[96:111], v[154:157], v[132:135], v[96:111]
	v_exp_f32_e32 v155, v66
	v_exp_f32_e32 v156, v67
	v_exp_f32_e32 v157, v68
	v_mfma_f32_32x32x16_bf16 v[96:111], v[212:215], v[128:131], v[96:111]
	v_exp_f32_e32 v212, v72
	v_exp_f32_e32 v213, v73
	v_exp_f32_e32 v214, v56
	v_exp_f32_e32 v215, v57
	v_mfma_f32_32x32x16_bf16 v[96:111], v[224:227], v[124:127], v[96:111]
	v_exp_f32_e32 v224, v77
	v_exp_f32_e32 v225, v60
	v_exp_f32_e32 v226, v61
	v_exp_f32_e32 v227, v78
	v_mfma_f32_32x32x16_bf16 v[96:111], v[232:235], v[120:123], v[96:111]
	v_mfma_f32_32x32x16_bf16 v[96:111], v[240:243], v[116:119], v[96:111]
	v_mfma_f32_32x32x16_bf16 v[80:95], v[202:205], v[132:135], v[80:95]
	v_exp_f32_e32 v202, v53
	v_exp_f32_e32 v203, v70
	v_exp_f32_e32 v204, v71
	v_exp_f32_e32 v205, v54
	v_mfma_f32_32x32x16_bf16 v[80:95], v[220:223], v[128:131], v[80:95]
	v_exp_f32_e32 v220, v75
	v_exp_f32_e32 v221, v58
	v_exp_f32_e32 v222, v59
	v_exp_f32_e32 v223, v76
	v_mfma_f32_32x32x16_bf16 v[80:95], v[228:231], v[124:127], v[80:95]
	v_exp_f32_e32 v228, v79
	v_exp_f32_e32 v229, v62
	v_exp_f32_e32 v230, v63
	v_mfma_f32_32x32x16_bf16 v[80:95], v[236:239], v[120:123], v[80:95]
	ds_read_b128 v[48:51], v173 offset:49152
	ds_read_b128 v[52:55], v173 offset:53248
	ds_read_b128 v[56:59], v197 offset:49152
	ds_read_b128 v[60:63], v197 offset:53248
	ds_read_b128 v[64:67], v193 offset:49152
	ds_read_b128 v[68:71], v193 offset:53248
	ds_read_b128 v[72:75], v195 offset:49152
	ds_read_b128 v[76:79], v195 offset:53248
	v_add_f32_e32 v32, v32, v150
	v_add_f32_e32 v33, v33, v151
	v_cvt_pk_bf16_f32 v154, v150, v151
	v_add_f32_e32 v34, v34, v155
	v_add_f32_e32 v35, v35, v156
	v_cvt_pk_bf16_f32 v155, v155, v156
	v_add_f32_e32 v32, v32, v157
	v_add_f32_e32 v33, v33, v201
	v_cvt_pk_bf16_f32 v156, v157, v201
	v_add_f32_e32 v34, v34, v203
	v_add_f32_e32 v35, v35, v204
	v_cvt_pk_bf16_f32 v157, v203, v204
	v_mfma_f32_32x32x16_bf16 v[80:95], v[244:247], v[116:119], v[80:95]
	s_and_b64 vcc, exec, s[6:7]
	s_waitcnt lgkmcnt(0)
	v_mfma_f32_32x32x16_bf16 v[16:31], v[52:55], v[154:157], v[16:31]
	v_mfma_f32_32x32x16_bf16 v[0:15], v[48:51], v[154:157], v[0:15]
	v_add_f32_e32 v32, v32, v212
	v_add_f32_e32 v33, v33, v213
	v_cvt_pk_bf16_f32 v48, v212, v213
	v_add_f32_e32 v34, v34, v219
	v_add_f32_e32 v35, v35, v220
	v_cvt_pk_bf16_f32 v49, v219, v220
	v_add_f32_e32 v32, v32, v223
	v_add_f32_e32 v33, v33, v224
	v_cvt_pk_bf16_f32 v50, v223, v224
	v_cvt_pk_bf16_f32 v51, v227, v228
	v_add_f32_e32 v34, v34, v227
	v_add_f32_e32 v35, v35, v228
	v_mfma_f32_32x32x16_bf16 v[16:31], v[60:63], v[48:51], v[16:31]
	v_mfma_f32_32x32x16_bf16 v[0:15], v[56:59], v[48:51], v[0:15]
	v_add_f32_e32 v32, v32, v152
	v_add_f32_e32 v33, v33, v153
	v_cvt_pk_bf16_f32 v52, v152, v153
	v_add_f32_e32 v34, v34, v167
	v_add_f32_e32 v35, v35, v169
	v_cvt_pk_bf16_f32 v53, v167, v169
	v_add_f32_e32 v32, v32, v208
	v_add_f32_e32 v33, v33, v202
	v_cvt_pk_bf16_f32 v54, v208, v202
	v_cvt_pk_bf16_f32 v55, v205, v209
	v_add_f32_e32 v34, v34, v205
	v_add_f32_e32 v35, v35, v209
	v_mfma_f32_32x32x16_bf16 v[16:31], v[68:71], v[52:55], v[16:31]
	v_mfma_f32_32x32x16_bf16 v[0:15], v[64:67], v[52:55], v[0:15]
	v_add_f32_e32 v32, v32, v214
	v_add_f32_e32 v33, v33, v215
	v_cvt_pk_bf16_f32 v48, v214, v215
	v_add_f32_e32 v34, v34, v221
	v_add_f32_e32 v35, v35, v222
	v_cvt_pk_bf16_f32 v49, v221, v222
	v_add_f32_e32 v32, v32, v225
	v_add_f32_e32 v33, v33, v226
	v_cvt_pk_bf16_f32 v50, v225, v226
	v_cvt_pk_bf16_f32 v51, v229, v230
	v_add_f32_e32 v34, v34, v229
	v_add_f32_e32 v35, v35, v230
	v_mfma_f32_32x32x16_bf16 v[16:31], v[76:79], v[48:51], v[16:31]
	v_mfma_f32_32x32x16_bf16 v[0:15], v[72:75], v[48:51], v[0:15]
	s_cbranch_vccz .Lmla_nf_0

.Lmla_late_skip0:
	s_and_b64 vcc, exec, s[6:7]
	s_waitcnt lgkmcnt(0)
	v_mfma_f32_32x32x16_bf16 v[16:31], v[84:87], v[154:157], v[16:31]
	v_mfma_f32_32x32x16_bf16 v[0:15], v[80:83], v[154:157], v[0:15]
	v_add_f32_e32 v32, v32, v212
	v_add_f32_e32 v33, v33, v213
	v_cvt_pk_bf16_f32 v80, v212, v213
	v_add_f32_e32 v34, v34, v219
	v_add_f32_e32 v35, v35, v220
	v_cvt_pk_bf16_f32 v81, v219, v220
	v_add_f32_e32 v32, v32, v223
	v_add_f32_e32 v33, v33, v224
	v_cvt_pk_bf16_f32 v82, v223, v224
	v_cvt_pk_bf16_f32 v83, v227, v228
	v_add_f32_e32 v34, v34, v227
	v_add_f32_e32 v35, v35, v228
	v_mfma_f32_32x32x16_bf16 v[16:31], v[92:95], v[80:83], v[16:31]
	v_mfma_f32_32x32x16_bf16 v[0:15], v[88:91], v[80:83], v[0:15]
	v_add_f32_e32 v32, v32, v152
	v_add_f32_e32 v33, v33, v153
	v_cvt_pk_bf16_f32 v84, v152, v153
	v_add_f32_e32 v34, v34, v167
	v_add_f32_e32 v35, v35, v169
	v_cvt_pk_bf16_f32 v85, v167, v169
	v_add_f32_e32 v32, v32, v208
	v_add_f32_e32 v33, v33, v202
	v_cvt_pk_bf16_f32 v86, v208, v202
	v_cvt_pk_bf16_f32 v87, v205, v209
	v_add_f32_e32 v34, v34, v205
	v_add_f32_e32 v35, v35, v209
	v_mfma_f32_32x32x16_bf16 v[16:31], v[100:103], v[84:87], v[16:31]
	v_mfma_f32_32x32x16_bf16 v[0:15], v[96:99], v[84:87], v[0:15]
	v_add_f32_e32 v32, v32, v214
	v_add_f32_e32 v33, v33, v215
	v_cvt_pk_bf16_f32 v80, v214, v215
	v_add_f32_e32 v34, v34, v221
	v_add_f32_e32 v35, v35, v222
	v_cvt_pk_bf16_f32 v81, v221, v222
	v_add_f32_e32 v32, v32, v225
	v_add_f32_e32 v33, v33, v226
	v_cvt_pk_bf16_f32 v82, v225, v226
	v_cvt_pk_bf16_f32 v83, v229, v230
	v_add_f32_e32 v34, v34, v229
	v_add_f32_e32 v35, v35, v230
	v_mfma_f32_32x32x16_bf16 v[16:31], v[108:111], v[80:83], v[16:31]
	v_mfma_f32_32x32x16_bf16 v[0:15], v[104:107], v[80:83], v[0:15]
	s_cbranch_vccz .Lmla_nf_1

.LBB0_1203:
	s_mov_b32 m0, s14
	s_mov_b64 s[14:15], 0x3600280
	global_load_lds_dwordx4 v[82:83], off
	v_lshl_add_u64 v[80:81], v[188:189], 0, s[14:15]
	s_sub_i32 m0, s62, s66
	s_add_i32 m0, m0, 0x8000
	v_exp_f32_e32 v150, v64
	global_load_lds_dwordx4 v[80:81], off
	ds_read_b128 v[80:83], v199 offset:36864
	ds_read_b128 v[84:87], v199 offset:43008
	ds_read_b128 v[154:157], v200 offset:36864
	ds_read_b128 v[186:189], v200 offset:43008
	ds_read_b128 v[202:205], v199 offset:36928
	ds_read_b128 v[212:215], v199 offset:43072
	ds_read_b128 v[220:223], v200 offset:36928
	ds_read_b128 v[224:227], v200 offset:43072
	ds_read_b128 v[228:231], v199 offset:36992
	ds_read_b128 v[232:235], v199 offset:43136
	ds_read_b128 v[236:239], v200 offset:36992
	ds_read_b128 v[240:243], v200 offset:43136
	s_waitcnt lgkmcnt(0)
	v_mfma_f32_32x32x16_bf16 v[96:111], v[80:83], v[136:139], 0
	v_exp_f32_e32 v151, v65
	v_exp_f32_e32 v152, v48
	v_exp_f32_e32 v153, v49
	v_exp_f32_e32 v167, v50
	v_exp_f32_e32 v169, v51
	v_exp_f32_e32 v190, v69
	v_exp_f32_e32 v191, v52
	v_mfma_f32_32x32x16_bf16 v[80:95], v[84:87], v[136:139], 0
	v_exp_f32_e32 v201, v55
	v_exp_f32_e32 v208, v74
	v_exp_f32_e32 v209, v75
	v_exp_f32_e32 v219, v60
	v_mfma_f32_32x32x16_bf16 v[96:111], v[154:157], v[132:135], v[96:111]
	v_exp_f32_e32 v155, v66
	v_exp_f32_e32 v156, v67
	v_exp_f32_e32 v157, v68
	v_mfma_f32_32x32x16_bf16 v[96:111], v[202:205], v[128:131], v[96:111]
	v_exp_f32_e32 v202, v72
	v_exp_f32_e32 v203, v73
	v_exp_f32_e32 v204, v56
	v_exp_f32_e32 v205, v57
	v_mfma_f32_32x32x16_bf16 v[96:111], v[220:223], v[124:127], v[96:111]
	v_exp_f32_e32 v220, v61
	v_exp_f32_e32 v221, v78
	v_exp_f32_e32 v222, v79
	v_exp_f32_e32 v223, v62
	v_mfma_f32_32x32x16_bf16 v[96:111], v[228:231], v[120:123], v[96:111]
	v_mfma_f32_32x32x16_bf16 v[96:111], v[236:239], v[116:119], v[96:111]
	v_mfma_f32_32x32x16_bf16 v[80:95], v[186:189], v[132:135], v[80:95]
	v_exp_f32_e32 v186, v53
	v_exp_f32_e32 v187, v70
	v_exp_f32_e32 v188, v71
	v_exp_f32_e32 v189, v54
	v_mfma_f32_32x32x16_bf16 v[80:95], v[212:215], v[128:131], v[80:95]
	v_exp_f32_e32 v212, v58
	v_exp_f32_e32 v213, v59
	v_exp_f32_e32 v214, v76
	v_exp_f32_e32 v215, v77
	v_mfma_f32_32x32x16_bf16 v[80:95], v[224:227], v[124:127], v[80:95]
	v_exp_f32_e32 v224, v63
	v_mfma_f32_32x32x16_bf16 v[80:95], v[232:235], v[120:123], v[80:95]
	ds_read_b128 v[48:51], v192 offset:16384
	ds_read_b128 v[52:55], v192 offset:20480
	ds_read_b128 v[56:59], v198 offset:16384
	ds_read_b128 v[60:63], v198 offset:20480
	ds_read_b128 v[64:67], v194 offset:16384
	ds_read_b128 v[68:71], v194 offset:20480
	ds_read_b128 v[72:75], v196 offset:16384
	ds_read_b128 v[76:79], v196 offset:20480
	v_add_f32_e32 v32, v32, v150
	v_add_f32_e32 v33, v33, v151
	v_cvt_pk_bf16_f32 v154, v150, v151
	v_add_f32_e32 v34, v34, v155
	v_add_f32_e32 v35, v35, v156
	v_cvt_pk_bf16_f32 v155, v155, v156
	v_add_f32_e32 v32, v32, v157
	v_add_f32_e32 v33, v33, v190
	v_cvt_pk_bf16_f32 v156, v157, v190
	v_add_f32_e32 v34, v34, v187
	v_add_f32_e32 v35, v35, v188
	v_cvt_pk_bf16_f32 v157, v187, v188
	v_mfma_f32_32x32x16_bf16 v[80:95], v[240:243], v[116:119], v[80:95]
	s_and_b64 vcc, exec, s[6:7]
	s_waitcnt lgkmcnt(0)
	v_mfma_f32_32x32x16_bf16 v[16:31], v[52:55], v[154:157], v[16:31]
	v_mfma_f32_32x32x16_bf16 v[0:15], v[48:51], v[154:157], v[0:15]
	v_add_f32_e32 v32, v32, v202
	v_add_f32_e32 v33, v33, v203
	v_cvt_pk_bf16_f32 v48, v202, v203
	v_add_f32_e32 v34, v34, v208
	v_add_f32_e32 v35, v35, v209
	v_cvt_pk_bf16_f32 v49, v208, v209
	v_add_f32_e32 v32, v32, v214
	v_add_f32_e32 v33, v33, v215
	v_cvt_pk_bf16_f32 v50, v214, v215
	v_cvt_pk_bf16_f32 v51, v221, v222
	v_add_f32_e32 v34, v34, v221
	v_add_f32_e32 v35, v35, v222
	v_mfma_f32_32x32x16_bf16 v[16:31], v[60:63], v[48:51], v[16:31]
	v_mfma_f32_32x32x16_bf16 v[0:15], v[56:59], v[48:51], v[0:15]
	v_add_f32_e32 v32, v32, v152
	v_add_f32_e32 v33, v33, v153
	v_cvt_pk_bf16_f32 v52, v152, v153
	v_add_f32_e32 v34, v34, v167
	v_add_f32_e32 v35, v35, v169
	v_cvt_pk_bf16_f32 v53, v167, v169
	v_add_f32_e32 v32, v32, v191
	v_add_f32_e32 v33, v33, v186
	v_cvt_pk_bf16_f32 v54, v191, v186
	v_cvt_pk_bf16_f32 v55, v189, v201
	v_add_f32_e32 v34, v34, v189
	v_add_f32_e32 v35, v35, v201
	v_mfma_f32_32x32x16_bf16 v[16:31], v[68:71], v[52:55], v[16:31]
	v_mfma_f32_32x32x16_bf16 v[0:15], v[64:67], v[52:55], v[0:15]
	v_add_f32_e32 v32, v32, v204
	v_add_f32_e32 v33, v33, v205
	v_cvt_pk_bf16_f32 v48, v204, v205
	v_add_f32_e32 v34, v34, v212
	v_add_f32_e32 v35, v35, v213
	v_cvt_pk_bf16_f32 v49, v212, v213
	v_add_f32_e32 v32, v32, v219
	v_add_f32_e32 v33, v33, v220
	v_cvt_pk_bf16_f32 v50, v219, v220
	v_cvt_pk_bf16_f32 v51, v223, v224
	v_add_f32_e32 v34, v34, v223
	v_add_f32_e32 v35, v35, v224
	v_mfma_f32_32x32x16_bf16 v[16:31], v[76:79], v[48:51], v[16:31]
	v_mfma_f32_32x32x16_bf16 v[0:15], v[72:75], v[48:51], v[0:15]
	s_cbranch_vccz .Lmla_nf_2

.LBB0_1213:
	s_mov_b32 m0, s12
	v_lshl_add_u64 v[80:81], v[84:85], 0, s[8:9]
	s_mov_b64 s[8:9], 0x1f80
	global_load_lds_dwordx4 v[80:81], off
	v_lshl_add_u64 v[80:81], v[178:179], 0, s[8:9]
	s_add_i32 m0, s17, s66
	v_exp_f32_e32 v150, v64
	global_load_lds_dwordx4 v[80:81], off
	ds_read_b128 v[80:83], v199 offset:12288
	ds_read_b128 v[84:87], v199 offset:18432
	ds_read_b128 v[154:157], v200 offset:12288
	ds_read_b128 v[176:179], v200 offset:18432
	ds_read_b128 v[180:183], v199 offset:12352
	ds_read_b128 v[184:187], v199 offset:18496
	ds_read_b128 v[188:191], v200 offset:12352
	ds_read_b128 v[202:205], v200 offset:18496
	ds_read_b128 v[212:215], v199 offset:12416
	ds_read_b128 v[220:223], v199 offset:18560
	ds_read_b128 v[224:227], v200 offset:12416
	ds_read_b128 v[228:231], v200 offset:18560
	s_waitcnt lgkmcnt(0)
	v_mfma_f32_32x32x16_bf16 v[96:111], v[80:83], v[136:139], 0
	v_exp_f32_e32 v151, v65
	v_exp_f32_e32 v152, v48
	v_exp_f32_e32 v153, v49
	v_exp_f32_e32 v167, v50
	v_exp_f32_e32 v169, v51
	v_exp_f32_e32 v201, v77
	v_exp_f32_e32 v208, v62
	v_mfma_f32_32x32x16_bf16 v[80:95], v[84:87], v[136:139], 0
	v_exp_f32_e32 v209, v63
	v_mfma_f32_32x32x16_bf16 v[96:111], v[154:157], v[132:135], v[96:111]
	v_exp_f32_e32 v155, v66
	v_exp_f32_e32 v156, v67
	v_exp_f32_e32 v157, v68
	v_mfma_f32_32x32x16_bf16 v[96:111], v[180:183], v[128:131], v[96:111]
	v_exp_f32_e32 v180, v69
	v_exp_f32_e32 v181, v52
	v_exp_f32_e32 v182, v55
	v_exp_f32_e32 v183, v72
	v_mfma_f32_32x32x16_bf16 v[96:111], v[188:191], v[124:127], v[96:111]
	v_exp_f32_e32 v188, v73
	v_exp_f32_e32 v189, v58
	v_exp_f32_e32 v190, v59
	v_exp_f32_e32 v191, v76
	v_mfma_f32_32x32x16_bf16 v[96:111], v[212:215], v[120:123], v[96:111]
	v_mfma_f32_32x32x16_bf16 v[96:111], v[224:227], v[116:119], v[96:111]
	v_mfma_f32_32x32x16_bf16 v[80:95], v[176:179], v[132:135], v[80:95]
	v_exp_f32_e32 v176, v53
	v_exp_f32_e32 v177, v70
	v_exp_f32_e32 v178, v71
	v_exp_f32_e32 v179, v54
	v_mfma_f32_32x32x16_bf16 v[80:95], v[184:187], v[128:131], v[80:95]
	v_exp_f32_e32 v184, v56
	v_exp_f32_e32 v185, v57
	v_exp_f32_e32 v186, v74
	v_exp_f32_e32 v187, v75
	v_mfma_f32_32x32x16_bf16 v[80:95], v[202:205], v[124:127], v[80:95]
	v_exp_f32_e32 v202, v60
	v_exp_f32_e32 v203, v61
	v_exp_f32_e32 v204, v78
	v_exp_f32_e32 v205, v79
	v_mfma_f32_32x32x16_bf16 v[80:95], v[220:223], v[120:123], v[80:95]
	ds_read_b128 v[48:51], v173 offset:49152
	ds_read_b128 v[52:55], v173 offset:53248
	ds_read_b128 v[56:59], v197 offset:49152
	ds_read_b128 v[60:63], v197 offset:53248
	ds_read_b128 v[64:67], v193 offset:49152
	ds_read_b128 v[68:71], v193 offset:53248
	ds_read_b128 v[72:75], v195 offset:49152
	ds_read_b128 v[76:79], v195 offset:53248
	v_add_f32_e32 v32, v32, v150
	v_add_f32_e32 v33, v33, v151
	v_cvt_pk_bf16_f32 v154, v150, v151
	v_add_f32_e32 v34, v34, v155
	v_add_f32_e32 v35, v35, v156
	v_cvt_pk_bf16_f32 v155, v155, v156
	v_add_f32_e32 v32, v32, v157
	v_add_f32_e32 v33, v33, v180
	v_cvt_pk_bf16_f32 v156, v157, v180
	v_add_f32_e32 v34, v34, v177
	v_add_f32_e32 v35, v35, v178
	v_cvt_pk_bf16_f32 v157, v177, v178
	v_mfma_f32_32x32x16_bf16 v[80:95], v[228:231], v[116:119], v[80:95]
	s_and_b64 vcc, exec, s[6:7]
	s_waitcnt lgkmcnt(0)
	v_mfma_f32_32x32x16_bf16 v[16:31], v[52:55], v[154:157], v[16:31]
	v_mfma_f32_32x32x16_bf16 v[0:15], v[48:51], v[154:157], v[0:15]
	v_add_f32_e32 v32, v32, v183
	v_add_f32_e32 v33, v33, v188
	v_cvt_pk_bf16_f32 v48, v183, v188
	v_add_f32_e32 v34, v34, v186
	v_add_f32_e32 v35, v35, v187
	v_cvt_pk_bf16_f32 v49, v186, v187
	v_add_f32_e32 v32, v32, v191
	v_add_f32_e32 v33, v33, v201
	v_cvt_pk_bf16_f32 v50, v191, v201
	v_cvt_pk_bf16_f32 v51, v204, v205
	v_add_f32_e32 v34, v34, v204
	v_add_f32_e32 v35, v35, v205
	v_mfma_f32_32x32x16_bf16 v[16:31], v[60:63], v[48:51], v[16:31]
	v_mfma_f32_32x32x16_bf16 v[0:15], v[56:59], v[48:51], v[0:15]
	v_add_f32_e32 v32, v32, v152
	v_add_f32_e32 v33, v33, v153
	v_cvt_pk_bf16_f32 v52, v152, v153
	v_add_f32_e32 v34, v34, v167
	v_add_f32_e32 v35, v35, v169
	v_cvt_pk_bf16_f32 v53, v167, v169
	v_add_f32_e32 v32, v32, v181
	v_add_f32_e32 v33, v33, v176
	v_cvt_pk_bf16_f32 v54, v181, v176
	v_cvt_pk_bf16_f32 v55, v179, v182
	v_add_f32_e32 v34, v34, v179
	v_add_f32_e32 v35, v35, v182
	v_mfma_f32_32x32x16_bf16 v[16:31], v[68:71], v[52:55], v[16:31]
	v_mfma_f32_32x32x16_bf16 v[0:15], v[64:67], v[52:55], v[0:15]
	v_add_f32_e32 v32, v32, v184
	v_add_f32_e32 v33, v33, v185
	v_cvt_pk_bf16_f32 v48, v184, v185
	v_add_f32_e32 v34, v34, v189
	v_add_f32_e32 v35, v35, v190
	v_cvt_pk_bf16_f32 v49, v189, v190
	v_add_f32_e32 v32, v32, v202
	v_add_f32_e32 v33, v33, v203
	v_cvt_pk_bf16_f32 v50, v202, v203
	v_cvt_pk_bf16_f32 v51, v208, v209
	v_add_f32_e32 v34, v34, v208
	v_add_f32_e32 v35, v35, v209
	v_mfma_f32_32x32x16_bf16 v[16:31], v[76:79], v[48:51], v[16:31]
	v_mfma_f32_32x32x16_bf16 v[0:15], v[72:75], v[48:51], v[0:15]
	s_cbranch_vccz .Lmla_nf_3

.Lmla_late_skip2:
	s_and_b64 vcc, exec, s[6:7]
	s_waitcnt lgkmcnt(0)
	v_mfma_f32_32x32x16_bf16 v[16:31], v[84:87], v[154:157], v[16:31]
	v_mfma_f32_32x32x16_bf16 v[0:15], v[80:83], v[154:157], v[0:15]
	v_add_f32_e32 v32, v32, v183
	v_add_f32_e32 v33, v33, v188
	v_cvt_pk_bf16_f32 v80, v183, v188
	v_add_f32_e32 v34, v34, v186
	v_add_f32_e32 v35, v35, v187
	v_cvt_pk_bf16_f32 v81, v186, v187
	v_add_f32_e32 v32, v32, v191
	v_add_f32_e32 v33, v33, v201
	v_cvt_pk_bf16_f32 v82, v191, v201
	v_cvt_pk_bf16_f32 v83, v204, v205
	v_add_f32_e32 v34, v34, v204
	v_add_f32_e32 v35, v35, v205
	v_mfma_f32_32x32x16_bf16 v[16:31], v[92:95], v[80:83], v[16:31]
	v_mfma_f32_32x32x16_bf16 v[0:15], v[88:91], v[80:83], v[0:15]
	v_add_f32_e32 v32, v32, v152
	v_add_f32_e32 v33, v33, v153
	v_cvt_pk_bf16_f32 v84, v152, v153
	v_add_f32_e32 v34, v34, v167
	v_add_f32_e32 v35, v35, v169
	v_cvt_pk_bf16_f32 v85, v167, v169
	v_add_f32_e32 v32, v32, v181
	v_add_f32_e32 v33, v33, v176
	v_cvt_pk_bf16_f32 v86, v181, v176
	v_cvt_pk_bf16_f32 v87, v179, v182
	v_add_f32_e32 v34, v34, v179
	v_add_f32_e32 v35, v35, v182
	v_mfma_f32_32x32x16_bf16 v[16:31], v[100:103], v[84:87], v[16:31]
	v_mfma_f32_32x32x16_bf16 v[0:15], v[96:99], v[84:87], v[0:15]
	v_add_f32_e32 v32, v32, v184
	v_add_f32_e32 v33, v33, v185
	v_cvt_pk_bf16_f32 v80, v184, v185
	v_add_f32_e32 v34, v34, v189
	v_add_f32_e32 v35, v35, v190
	v_cvt_pk_bf16_f32 v81, v189, v190
	v_add_f32_e32 v32, v32, v202
	v_add_f32_e32 v33, v33, v203
	v_cvt_pk_bf16_f32 v82, v202, v203
	v_cvt_pk_bf16_f32 v83, v208, v209
	v_add_f32_e32 v34, v34, v208
	v_add_f32_e32 v35, v35, v209
	v_mfma_f32_32x32x16_bf16 v[16:31], v[108:111], v[80:83], v[16:31]
	v_mfma_f32_32x32x16_bf16 v[0:15], v[104:107], v[80:83], v[0:15]
	s_cbranch_vccz .Lmla_nf_4

.Lmla_early_skip2:
	s_sub_i32 m0, s60, s66
	s_add_i32 m0, m0, 0x8000
	v_exp_f32_e32 v150, v64
	global_load_lds_dwordx4 v[80:81], off
	ds_read_b128 v[80:83], v199 offset:36864
	ds_read_b128 v[84:87], v199 offset:43008
	ds_read_b128 v[154:157], v200 offset:36864
	ds_read_b128 v[174:177], v200 offset:43008
	ds_read_b128 v[178:181], v199 offset:36928
	ds_read_b128 v[182:185], v199 offset:43072
	ds_read_b128 v[186:189], v200 offset:36928
	ds_read_b128 v[202:205], v200 offset:43072
	ds_read_b128 v[212:215], v199 offset:36992
	ds_read_b128 v[220:223], v199 offset:43136
	ds_read_b128 v[224:227], v200 offset:36992
	ds_read_b128 v[228:231], v200 offset:43136
	s_waitcnt lgkmcnt(0)
	v_mfma_f32_32x32x16_bf16 v[96:111], v[80:83], v[136:139], 0
	v_exp_f32_e32 v151, v65
	v_exp_f32_e32 v152, v48
	v_exp_f32_e32 v153, v49
	v_exp_f32_e32 v167, v50
	v_exp_f32_e32 v169, v51
	v_exp_f32_e32 v190, v77
	v_exp_f32_e32 v191, v60
	v_mfma_f32_32x32x16_bf16 v[80:95], v[84:87], v[136:139], 0
	v_exp_f32_e32 v201, v61
	v_mfma_f32_32x32x16_bf16 v[96:111], v[154:157], v[132:135], v[96:111]
	v_exp_f32_e32 v155, v66
	v_exp_f32_e32 v156, v67
	v_exp_f32_e32 v157, v68
	v_mfma_f32_32x32x16_bf16 v[96:111], v[178:181], v[128:131], v[96:111]
	v_exp_f32_e32 v178, v69
	v_exp_f32_e32 v179, v52
	v_exp_f32_e32 v180, v55
	v_exp_f32_e32 v181, v72
	v_mfma_f32_32x32x16_bf16 v[96:111], v[186:189], v[124:127], v[96:111]
	v_exp_f32_e32 v186, v73
	v_exp_f32_e32 v187, v58
	v_exp_f32_e32 v188, v59
	v_exp_f32_e32 v189, v76
	v_mfma_f32_32x32x16_bf16 v[96:111], v[212:215], v[120:123], v[96:111]
	v_mfma_f32_32x32x16_bf16 v[96:111], v[224:227], v[116:119], v[96:111]
	v_mfma_f32_32x32x16_bf16 v[80:95], v[174:177], v[132:135], v[80:95]
	v_exp_f32_e32 v174, v53
	v_exp_f32_e32 v175, v70
	v_exp_f32_e32 v176, v71
	v_exp_f32_e32 v177, v54
	v_mfma_f32_32x32x16_bf16 v[80:95], v[182:185], v[128:131], v[80:95]
	v_exp_f32_e32 v182, v56
	v_exp_f32_e32 v183, v57
	v_exp_f32_e32 v184, v74
	v_exp_f32_e32 v185, v75
	v_mfma_f32_32x32x16_bf16 v[80:95], v[202:205], v[124:127], v[80:95]
	v_exp_f32_e32 v202, v78
	v_exp_f32_e32 v203, v79
	v_exp_f32_e32 v204, v62
	v_exp_f32_e32 v205, v63
	v_mfma_f32_32x32x16_bf16 v[80:95], v[220:223], v[120:123], v[80:95]
	ds_read_b128 v[48:51], v192 offset:16384
	ds_read_b128 v[52:55], v192 offset:20480
	ds_read_b128 v[56:59], v198 offset:16384
	ds_read_b128 v[60:63], v198 offset:20480
	ds_read_b128 v[64:67], v194 offset:16384
	ds_read_b128 v[68:71], v194 offset:20480
	ds_read_b128 v[72:75], v196 offset:16384
	ds_read_b128 v[76:79], v196 offset:20480
	v_add_f32_e32 v32, v32, v150
	v_add_f32_e32 v33, v33, v151
	v_cvt_pk_bf16_f32 v154, v150, v151
	v_add_f32_e32 v34, v34, v155
	v_add_f32_e32 v35, v35, v156
	v_cvt_pk_bf16_f32 v155, v155, v156
	v_add_f32_e32 v32, v32, v157
	v_add_f32_e32 v33, v33, v178
	v_cvt_pk_bf16_f32 v156, v157, v178
	v_add_f32_e32 v34, v34, v175
	v_add_f32_e32 v35, v35, v176
	v_cvt_pk_bf16_f32 v157, v175, v176
	v_mfma_f32_32x32x16_bf16 v[80:95], v[228:231], v[116:119], v[80:95]
	s_and_b64 vcc, exec, s[6:7]
	s_waitcnt lgkmcnt(0)
	v_mfma_f32_32x32x16_bf16 v[16:31], v[52:55], v[154:157], v[16:31]
	v_mfma_f32_32x32x16_bf16 v[0:15], v[48:51], v[154:157], v[0:15]
	v_add_f32_e32 v32, v32, v181
	v_add_f32_e32 v33, v33, v186
	v_cvt_pk_bf16_f32 v48, v181, v186
	v_add_f32_e32 v34, v34, v184
	v_add_f32_e32 v35, v35, v185
	v_cvt_pk_bf16_f32 v49, v184, v185
	v_add_f32_e32 v32, v32, v189
	v_add_f32_e32 v33, v33, v190
	v_cvt_pk_bf16_f32 v50, v189, v190
	v_cvt_pk_bf16_f32 v51, v202, v203
	v_add_f32_e32 v34, v34, v202
	v_add_f32_e32 v35, v35, v203
	v_mfma_f32_32x32x16_bf16 v[16:31], v[60:63], v[48:51], v[16:31]
	v_mfma_f32_32x32x16_bf16 v[0:15], v[56:59], v[48:51], v[0:15]
	v_add_f32_e32 v32, v32, v152
	v_add_f32_e32 v33, v33, v153
	v_cvt_pk_bf16_f32 v52, v152, v153
	v_add_f32_e32 v34, v34, v167
	v_add_f32_e32 v35, v35, v169
	v_cvt_pk_bf16_f32 v53, v167, v169
	v_add_f32_e32 v32, v32, v179
	v_add_f32_e32 v33, v33, v174
	v_cvt_pk_bf16_f32 v54, v179, v174
	v_cvt_pk_bf16_f32 v55, v177, v180
	v_add_f32_e32 v34, v34, v177
	v_add_f32_e32 v35, v35, v180
	v_mfma_f32_32x32x16_bf16 v[16:31], v[68:71], v[52:55], v[16:31]
	v_mfma_f32_32x32x16_bf16 v[0:15], v[64:67], v[52:55], v[0:15]
	v_add_f32_e32 v32, v32, v182
	v_add_f32_e32 v33, v33, v183
	v_cvt_pk_bf16_f32 v48, v182, v183
	v_add_f32_e32 v34, v34, v187
	v_add_f32_e32 v35, v35, v188
	v_cvt_pk_bf16_f32 v49, v187, v188
	v_add_f32_e32 v32, v32, v191
	v_add_f32_e32 v33, v33, v201
	v_cvt_pk_bf16_f32 v50, v191, v201
	v_cvt_pk_bf16_f32 v51, v204, v205
	v_add_f32_e32 v34, v34, v204
	v_add_f32_e32 v35, v35, v205
	v_mfma_f32_32x32x16_bf16 v[16:31], v[76:79], v[48:51], v[16:31]
	v_mfma_f32_32x32x16_bf16 v[0:15], v[72:75], v[48:51], v[0:15]
	s_cbranch_vccz .Lmla_nf_5

.Lmla_late_skip3:
	s_and_b64 vcc, exec, s[6:7]
	s_waitcnt lgkmcnt(0)
	v_mfma_f32_32x32x16_bf16 v[16:31], v[60:63], v[88:91], v[16:31]
	v_mfma_f32_32x32x16_bf16 v[0:15], v[56:59], v[88:91], v[0:15]
	v_add_f32_e32 v32, v32, v104
	v_add_f32_e32 v33, v33, v105
	v_cvt_pk_bf16_f32 v56, v104, v105
	v_add_f32_e32 v34, v34, v106
	v_add_f32_e32 v35, v35, v107
	v_cvt_pk_bf16_f32 v57, v106, v107
	v_add_f32_e32 v32, v32, v108
	v_add_f32_e32 v33, v33, v109
	v_cvt_pk_bf16_f32 v58, v108, v109
	v_add_f32_e32 v34, v34, v110
	v_add_f32_e32 v35, v35, v111
	v_cvt_pk_bf16_f32 v59, v110, v111
	s_nop 1
	v_mfma_f32_32x32x16_bf16 v[16:31], v[68:71], v[56:59], v[16:31]
	v_mfma_f32_32x32x16_bf16 v[0:15], v[64:67], v[56:59], v[0:15]
	v_add_f32_e32 v32, v32, v136
	v_add_f32_e32 v33, v33, v137
	v_cvt_pk_bf16_f32 v56, v136, v137
	v_add_f32_e32 v34, v34, v132
	v_add_f32_e32 v35, v35, v133
	v_cvt_pk_bf16_f32 v57, v132, v133
	v_add_f32_e32 v32, v32, v134
	v_add_f32_e32 v33, v33, v128
	v_cvt_pk_bf16_f32 v58, v134, v128
	v_add_f32_e32 v34, v34, v129
	v_add_f32_e32 v35, v35, v130
	v_cvt_pk_bf16_f32 v59, v129, v130
	s_nop 1
	v_mfma_f32_32x32x16_bf16 v[16:31], v[76:79], v[56:59], v[16:31]
	v_mfma_f32_32x32x16_bf16 v[0:15], v[72:75], v[56:59], v[0:15]
	v_add_f32_e32 v32, v32, v124
	v_add_f32_e32 v33, v33, v125
	v_cvt_pk_bf16_f32 v56, v124, v125
	v_add_f32_e32 v34, v34, v126
	v_add_f32_e32 v35, v35, v127
	v_cvt_pk_bf16_f32 v57, v126, v127
	v_add_f32_e32 v32, v32, v92
	v_add_f32_e32 v33, v33, v93
	v_cvt_pk_bf16_f32 v58, v92, v93
	v_add_f32_e32 v34, v34, v94
	v_add_f32_e32 v35, v35, v95
	v_cvt_pk_bf16_f32 v59, v94, v95
	s_nop 1
	v_mfma_f32_32x32x16_bf16 v[16:31], v[84:87], v[56:59], v[16:31]
	v_mfma_f32_32x32x16_bf16 v[0:15], v[80:83], v[56:59], v[0:15]
	s_cbranch_vccnz .LBB0_1176
	v_pk_add_f32 v[50:51], v[50:51], v[172:173] op_sel_hi:[1,0] neg_lo:[0,1] neg_hi:[0,1]
	v_pk_add_f32 v[54:55], v[54:55], v[172:173] op_sel_hi:[1,0] neg_lo:[0,1] neg_hi:[0,1]
	v_pk_add_f32 v[48:49], v[48:49], v[172:173] op_sel_hi:[1,0] neg_lo:[0,1] neg_hi:[0,1]
	v_pk_add_f32 v[52:53], v[52:53], v[172:173] op_sel_hi:[1,0] neg_lo:[0,1] neg_hi:[0,1]
	v_max_f32_e32 v57, v50, v51
	v_max_f32_e32 v58, v54, v55
	v_sub_f32_e32 v56, 0xff800000, v172
	v_max3_f32 v57, v48, v49, v57
	v_max3_f32 v58, v52, v53, v58
	v_max3_f32 v57, v57, v58, v56
	ds_bpermute_b32 v58, v218, v57
	s_mov_b32 s6, 0x41000000
	s_waitcnt lgkmcnt(0)
	v_max_f32_e32 v58, v58, v58
	v_max_f32_e32 v57, v57, v58
	v_cmp_lt_f32_e32 vcc, s6, v57
	s_cbranch_vccz .LBB0_1177
	v_max_f32_e32 v57, v57, v57
	v_max_f32_e32 v58, 0, v57
	v_exp_f32_e64 v60, -v58
	v_sub_f32_e32 v56, v56, v58
	v_pk_add_f32 v[48:49], v[48:49], v[58:59] op_sel_hi:[1,0] neg_lo:[0,1] neg_hi:[0,1]
	v_pk_add_f32 v[50:51], v[50:51], v[58:59] op_sel_hi:[1,0] neg_lo:[0,1] neg_hi:[0,1]
	v_pk_add_f32 v[52:53], v[52:53], v[58:59] op_sel_hi:[1,0] neg_lo:[0,1] neg_hi:[0,1]
	v_pk_add_f32 v[54:55], v[54:55], v[58:59] op_sel_hi:[1,0] neg_lo:[0,1] neg_hi:[0,1]
	v_pk_mul_f32 v[14:15], v[14:15], v[60:61] op_sel_hi:[1,0]
	v_pk_mul_f32 v[12:13], v[12:13], v[60:61] op_sel_hi:[1,0]
	v_pk_mul_f32 v[10:11], v[10:11], v[60:61] op_sel_hi:[1,0]
	v_pk_mul_f32 v[8:9], v[8:9], v[60:61] op_sel_hi:[1,0]
	v_pk_mul_f32 v[6:7], v[6:7], v[60:61] op_sel_hi:[1,0]
	v_pk_mul_f32 v[4:5], v[4:5], v[60:61] op_sel_hi:[1,0]
	v_pk_mul_f32 v[2:3], v[2:3], v[60:61] op_sel_hi:[1,0]
	v_pk_mul_f32 v[0:1], v[0:1], v[60:61] op_sel_hi:[1,0]
	v_pk_mul_f32 v[30:31], v[30:31], v[60:61] op_sel_hi:[1,0]
	v_pk_mul_f32 v[28:29], v[28:29], v[60:61] op_sel_hi:[1,0]
	v_pk_mul_f32 v[26:27], v[26:27], v[60:61] op_sel_hi:[1,0]
	v_pk_mul_f32 v[24:25], v[24:25], v[60:61] op_sel_hi:[1,0]
	v_pk_mul_f32 v[22:23], v[22:23], v[60:61] op_sel_hi:[1,0]
	v_pk_mul_f32 v[20:21], v[20:21], v[60:61] op_sel_hi:[1,0]
	v_pk_mul_f32 v[18:19], v[18:19], v[60:61] op_sel_hi:[1,0]
	v_pk_mul_f32 v[16:17], v[16:17], v[60:61] op_sel_hi:[1,0]
	v_pk_mul_f32 v[46:47], v[46:47], v[60:61] op_sel_hi:[1,0]
	v_pk_mul_f32 v[44:45], v[44:45], v[60:61] op_sel_hi:[1,0]
	v_pk_mul_f32 v[42:43], v[42:43], v[60:61] op_sel_hi:[1,0]
	v_pk_mul_f32 v[40:41], v[40:41], v[60:61] op_sel_hi:[1,0]
	v_pk_mul_f32 v[38:39], v[38:39], v[60:61] op_sel_hi:[1,0]
	v_pk_mul_f32 v[36:37], v[36:37], v[60:61] op_sel_hi:[1,0]
	v_pk_mul_f32 v[34:35], v[34:35], v[60:61] op_sel_hi:[1,0]
	v_pk_mul_f32 v[32:33], v[32:33], v[60:61] op_sel_hi:[1,0]
	s_branch .LBB0_1177
	s_branch .LBB0_1225
.Lmla_nf_0:
	v_pk_add_f32 v[102:103], v[102:103], v[172:173] op_sel_hi:[1,0] neg_lo:[0,1] neg_hi:[0,1]
	v_pk_add_f32 v[110:111], v[110:111], v[172:173] op_sel_hi:[1,0] neg_lo:[0,1] neg_hi:[0,1]
	v_pk_add_f32 v[96:97], v[96:97], v[172:173] op_sel_hi:[1,0] neg_lo:[0,1] neg_hi:[0,1]
	v_pk_add_f32 v[98:99], v[98:99], v[172:173] op_sel_hi:[1,0] neg_lo:[0,1] neg_hi:[0,1]
	v_pk_add_f32 v[100:101], v[100:101], v[172:173] op_sel_hi:[1,0] neg_lo:[0,1] neg_hi:[0,1]
	v_pk_add_f32 v[104:105], v[104:105], v[172:173] op_sel_hi:[1,0] neg_lo:[0,1] neg_hi:[0,1]
	v_pk_add_f32 v[106:107], v[106:107], v[172:173] op_sel_hi:[1,0] neg_lo:[0,1] neg_hi:[0,1]
	v_pk_add_f32 v[108:109], v[108:109], v[172:173] op_sel_hi:[1,0] neg_lo:[0,1] neg_hi:[0,1]
	v_pk_add_f32 v[94:95], v[94:95], v[172:173] op_sel_hi:[1,0] neg_lo:[0,1] neg_hi:[0,1]
	v_max_f32_e32 v50, v102, v103
	v_max_f32_e32 v53, v110, v111
	v_pk_add_f32 v[82:83], v[82:83], v[172:173] op_sel_hi:[1,0] neg_lo:[0,1] neg_hi:[0,1]
	v_pk_add_f32 v[86:87], v[86:87], v[172:173] op_sel_hi:[1,0] neg_lo:[0,1] neg_hi:[0,1]
	v_pk_add_f32 v[88:89], v[88:89], v[172:173] op_sel_hi:[1,0] neg_lo:[0,1] neg_hi:[0,1]
	v_pk_add_f32 v[90:91], v[90:91], v[172:173] op_sel_hi:[1,0] neg_lo:[0,1] neg_hi:[0,1]
	v_pk_add_f32 v[92:93], v[92:93], v[172:173] op_sel_hi:[1,0] neg_lo:[0,1] neg_hi:[0,1]
	v_max_f32_e32 v48, v96, v97
	v_max_f32_e32 v49, v98, v99
	v_max3_f32 v50, v100, v101, v50
	v_max_f32_e32 v51, v104, v105
	v_max_f32_e32 v52, v106, v107
	v_max3_f32 v53, v108, v109, v53
	v_max_f32_e32 v54, v94, v95
	v_pk_add_f32 v[80:81], v[80:81], v[172:173] op_sel_hi:[1,0] neg_lo:[0,1] neg_hi:[0,1]
	v_pk_add_f32 v[84:85], v[84:85], v[172:173] op_sel_hi:[1,0] neg_lo:[0,1] neg_hi:[0,1]
	v_max3_f32 v48, v48, v49, v50
	v_max3_f32 v49, v51, v52, v53
	v_max_f32_e32 v50, v82, v83
	v_max_f32_e32 v51, v86, v87
	v_max_f32_e32 v52, v88, v89
	v_max_f32_e32 v53, v90, v91
	v_max3_f32 v54, v92, v93, v54
	v_max3_f32 v50, v80, v81, v50
	v_max3_f32 v51, v84, v85, v51
	v_max3_f32 v52, v52, v53, v54
	v_max3_f32 v50, v50, v51, v52
	v_max3_f32 v48, v48, v49, v50
	ds_bpermute_b32 v49, v218, v48
	s_mov_b32 s14, 0x41000000
	s_waitcnt lgkmcnt(0)
	v_max_f32_e32 v49, v49, v49
	v_max_f32_e32 v48, v48, v49
	v_cmp_lt_f32_e32 vcc, s14, v48
	s_cbranch_vccz .LBB0_1196
	v_max_f32_e32 v48, v48, v48
	v_max_f32_e32 v49, 0, v48
	v_exp_f32_e64 v48, -v49
	v_sub_f32_e32 v96, v96, v49
	v_sub_f32_e32 v97, v97, v49
	v_sub_f32_e32 v98, v98, v49
	v_sub_f32_e32 v99, v99, v49
	v_sub_f32_e32 v100, v100, v49
	v_sub_f32_e32 v101, v101, v49
	v_sub_f32_e32 v102, v102, v49
	v_sub_f32_e32 v103, v103, v49
	v_sub_f32_e32 v104, v104, v49
	v_sub_f32_e32 v105, v105, v49
	v_sub_f32_e32 v106, v106, v49
	v_sub_f32_e32 v107, v107, v49
	v_sub_f32_e32 v108, v108, v49
	v_sub_f32_e32 v109, v109, v49
	v_sub_f32_e32 v110, v110, v49
	v_sub_f32_e32 v111, v111, v49
	v_sub_f32_e32 v80, v80, v49
	v_sub_f32_e32 v81, v81, v49
	v_sub_f32_e32 v82, v82, v49
	v_sub_f32_e32 v83, v83, v49
	v_sub_f32_e32 v84, v84, v49
	v_sub_f32_e32 v85, v85, v49
	v_sub_f32_e32 v86, v86, v49
	v_sub_f32_e32 v87, v87, v49
	v_sub_f32_e32 v88, v88, v49
	v_sub_f32_e32 v89, v89, v49
	v_sub_f32_e32 v90, v90, v49
	v_sub_f32_e32 v91, v91, v49
	v_sub_f32_e32 v92, v92, v49
	v_sub_f32_e32 v93, v93, v49
	v_sub_f32_e32 v94, v94, v49
	v_sub_f32_e32 v95, v95, v49
	v_pk_mul_f32 v[14:15], v[14:15], v[48:49] op_sel_hi:[1,0]
	v_pk_mul_f32 v[12:13], v[12:13], v[48:49] op_sel_hi:[1,0]
	v_pk_mul_f32 v[10:11], v[10:11], v[48:49] op_sel_hi:[1,0]
	v_pk_mul_f32 v[8:9], v[8:9], v[48:49] op_sel_hi:[1,0]
	v_pk_mul_f32 v[6:7], v[6:7], v[48:49] op_sel_hi:[1,0]
	v_pk_mul_f32 v[4:5], v[4:5], v[48:49] op_sel_hi:[1,0]
	v_pk_mul_f32 v[2:3], v[2:3], v[48:49] op_sel_hi:[1,0]
	v_pk_mul_f32 v[0:1], v[0:1], v[48:49] op_sel_hi:[1,0]
	v_pk_mul_f32 v[30:31], v[30:31], v[48:49] op_sel_hi:[1,0]
	v_pk_mul_f32 v[28:29], v[28:29], v[48:49] op_sel_hi:[1,0]
	v_pk_mul_f32 v[26:27], v[26:27], v[48:49] op_sel_hi:[1,0]
	v_pk_mul_f32 v[24:25], v[24:25], v[48:49] op_sel_hi:[1,0]
	v_pk_mul_f32 v[22:23], v[22:23], v[48:49] op_sel_hi:[1,0]
	v_pk_mul_f32 v[20:21], v[20:21], v[48:49] op_sel_hi:[1,0]
	v_pk_mul_f32 v[18:19], v[18:19], v[48:49] op_sel_hi:[1,0]
	v_pk_mul_f32 v[16:17], v[16:17], v[48:49] op_sel_hi:[1,0]
	v_pk_mul_f32 v[46:47], v[46:47], v[48:49] op_sel_hi:[1,0]
	v_pk_mul_f32 v[44:45], v[44:45], v[48:49] op_sel_hi:[1,0]
	v_pk_mul_f32 v[42:43], v[42:43], v[48:49] op_sel_hi:[1,0]
	v_pk_mul_f32 v[40:41], v[40:41], v[48:49] op_sel_hi:[1,0]
	v_pk_mul_f32 v[38:39], v[38:39], v[48:49] op_sel_hi:[1,0]
	v_pk_mul_f32 v[36:37], v[36:37], v[48:49] op_sel_hi:[1,0]
	v_pk_mul_f32 v[34:35], v[34:35], v[48:49] op_sel_hi:[1,0]
	v_pk_mul_f32 v[32:33], v[32:33], v[48:49] op_sel_hi:[1,0]
	v_add_f32_e32 v172, v172, v49
	s_branch .LBB0_1196
.Lmla_nf_1:
	v_pk_add_f32 v[70:71], v[70:71], v[172:173] op_sel_hi:[1,0] neg_lo:[0,1] neg_hi:[0,1]
	v_pk_add_f32 v[78:79], v[78:79], v[172:173] op_sel_hi:[1,0] neg_lo:[0,1] neg_hi:[0,1]
	v_pk_add_f32 v[64:65], v[64:65], v[172:173] op_sel_hi:[1,0] neg_lo:[0,1] neg_hi:[0,1]
	v_pk_add_f32 v[66:67], v[66:67], v[172:173] op_sel_hi:[1,0] neg_lo:[0,1] neg_hi:[0,1]
	v_pk_add_f32 v[68:69], v[68:69], v[172:173] op_sel_hi:[1,0] neg_lo:[0,1] neg_hi:[0,1]
	v_pk_add_f32 v[72:73], v[72:73], v[172:173] op_sel_hi:[1,0] neg_lo:[0,1] neg_hi:[0,1]
	v_pk_add_f32 v[74:75], v[74:75], v[172:173] op_sel_hi:[1,0] neg_lo:[0,1] neg_hi:[0,1]
	v_pk_add_f32 v[76:77], v[76:77], v[172:173] op_sel_hi:[1,0] neg_lo:[0,1] neg_hi:[0,1]
	v_pk_add_f32 v[62:63], v[62:63], v[172:173] op_sel_hi:[1,0] neg_lo:[0,1] neg_hi:[0,1]
	v_max_f32_e32 v82, v70, v71
	v_max_f32_e32 v85, v78, v79
	v_pk_add_f32 v[50:51], v[50:51], v[172:173] op_sel_hi:[1,0] neg_lo:[0,1] neg_hi:[0,1]
	v_pk_add_f32 v[54:55], v[54:55], v[172:173] op_sel_hi:[1,0] neg_lo:[0,1] neg_hi:[0,1]
	v_pk_add_f32 v[56:57], v[56:57], v[172:173] op_sel_hi:[1,0] neg_lo:[0,1] neg_hi:[0,1]
	v_pk_add_f32 v[58:59], v[58:59], v[172:173] op_sel_hi:[1,0] neg_lo:[0,1] neg_hi:[0,1]
	v_pk_add_f32 v[60:61], v[60:61], v[172:173] op_sel_hi:[1,0] neg_lo:[0,1] neg_hi:[0,1]
	v_max_f32_e32 v80, v64, v65
	v_max_f32_e32 v81, v66, v67
	v_max3_f32 v82, v68, v69, v82
	v_max_f32_e32 v83, v72, v73
	v_max_f32_e32 v84, v74, v75
	v_max3_f32 v85, v76, v77, v85
	v_max_f32_e32 v86, v62, v63
	v_pk_add_f32 v[48:49], v[48:49], v[172:173] op_sel_hi:[1,0] neg_lo:[0,1] neg_hi:[0,1]
	v_pk_add_f32 v[52:53], v[52:53], v[172:173] op_sel_hi:[1,0] neg_lo:[0,1] neg_hi:[0,1]
	v_max3_f32 v80, v80, v81, v82
	v_max3_f32 v81, v83, v84, v85
	v_max_f32_e32 v82, v50, v51
	v_max_f32_e32 v83, v54, v55
	v_max_f32_e32 v84, v56, v57
	v_max_f32_e32 v85, v58, v59
	v_max3_f32 v86, v60, v61, v86
	v_max3_f32 v82, v48, v49, v82
	v_max3_f32 v83, v52, v53, v83
	v_max3_f32 v84, v84, v85, v86
	v_max3_f32 v82, v82, v83, v84
	v_max3_f32 v80, v80, v81, v82
	ds_bpermute_b32 v81, v218, v80
	s_mov_b32 s14, 0x41000000
	s_waitcnt lgkmcnt(0)
	v_max_f32_e32 v81, v81, v81
	v_max_f32_e32 v80, v80, v81
	v_cmp_lt_f32_e32 vcc, s14, v80
	s_cbranch_vccz .LBB0_1199
	v_max_f32_e32 v80, v80, v80
	v_max_f32_e32 v81, 0, v80
	v_exp_f32_e64 v80, -v81
	v_sub_f32_e32 v64, v64, v81
	v_sub_f32_e32 v65, v65, v81
	v_sub_f32_e32 v66, v66, v81
	v_sub_f32_e32 v67, v67, v81
	v_sub_f32_e32 v68, v68, v81
	v_sub_f32_e32 v69, v69, v81
	v_sub_f32_e32 v70, v70, v81
	v_sub_f32_e32 v71, v71, v81
	v_sub_f32_e32 v72, v72, v81
	v_sub_f32_e32 v73, v73, v81
	v_sub_f32_e32 v74, v74, v81
	v_sub_f32_e32 v75, v75, v81
	v_sub_f32_e32 v76, v76, v81
	v_sub_f32_e32 v77, v77, v81
	v_sub_f32_e32 v78, v78, v81
	v_sub_f32_e32 v79, v79, v81
	v_sub_f32_e32 v48, v48, v81
	v_sub_f32_e32 v49, v49, v81
	v_sub_f32_e32 v50, v50, v81
	v_sub_f32_e32 v51, v51, v81
	v_sub_f32_e32 v52, v52, v81
	v_sub_f32_e32 v53, v53, v81
	v_sub_f32_e32 v54, v54, v81
	v_sub_f32_e32 v55, v55, v81
	v_sub_f32_e32 v56, v56, v81
	v_sub_f32_e32 v57, v57, v81
	v_sub_f32_e32 v58, v58, v81
	v_sub_f32_e32 v59, v59, v81
	v_sub_f32_e32 v60, v60, v81
	v_sub_f32_e32 v61, v61, v81
	v_sub_f32_e32 v62, v62, v81
	v_sub_f32_e32 v63, v63, v81
	v_pk_mul_f32 v[14:15], v[14:15], v[80:81] op_sel_hi:[1,0]
	v_pk_mul_f32 v[12:13], v[12:13], v[80:81] op_sel_hi:[1,0]
	v_pk_mul_f32 v[10:11], v[10:11], v[80:81] op_sel_hi:[1,0]
	v_pk_mul_f32 v[8:9], v[8:9], v[80:81] op_sel_hi:[1,0]
	v_pk_mul_f32 v[6:7], v[6:7], v[80:81] op_sel_hi:[1,0]
	v_pk_mul_f32 v[4:5], v[4:5], v[80:81] op_sel_hi:[1,0]
	v_pk_mul_f32 v[2:3], v[2:3], v[80:81] op_sel_hi:[1,0]
	v_pk_mul_f32 v[0:1], v[0:1], v[80:81] op_sel_hi:[1,0]
	v_pk_mul_f32 v[30:31], v[30:31], v[80:81] op_sel_hi:[1,0]
	v_pk_mul_f32 v[28:29], v[28:29], v[80:81] op_sel_hi:[1,0]
	v_pk_mul_f32 v[26:27], v[26:27], v[80:81] op_sel_hi:[1,0]
	v_pk_mul_f32 v[24:25], v[24:25], v[80:81] op_sel_hi:[1,0]
	v_pk_mul_f32 v[22:23], v[22:23], v[80:81] op_sel_hi:[1,0]
	v_pk_mul_f32 v[20:21], v[20:21], v[80:81] op_sel_hi:[1,0]
	v_pk_mul_f32 v[18:19], v[18:19], v[80:81] op_sel_hi:[1,0]
	v_pk_mul_f32 v[16:17], v[16:17], v[80:81] op_sel_hi:[1,0]
	v_pk_mul_f32 v[46:47], v[46:47], v[80:81] op_sel_hi:[1,0]
	v_pk_mul_f32 v[44:45], v[44:45], v[80:81] op_sel_hi:[1,0]
	v_pk_mul_f32 v[42:43], v[42:43], v[80:81] op_sel_hi:[1,0]
	v_pk_mul_f32 v[40:41], v[40:41], v[80:81] op_sel_hi:[1,0]
	v_pk_mul_f32 v[38:39], v[38:39], v[80:81] op_sel_hi:[1,0]
	v_pk_mul_f32 v[36:37], v[36:37], v[80:81] op_sel_hi:[1,0]
	v_pk_mul_f32 v[34:35], v[34:35], v[80:81] op_sel_hi:[1,0]
	v_pk_mul_f32 v[32:33], v[32:33], v[80:81] op_sel_hi:[1,0]
	v_add_f32_e32 v172, v172, v81
	s_branch .LBB0_1199

.Lmla_nf_3:
	v_pk_add_f32 v[102:103], v[102:103], v[172:173] op_sel_hi:[1,0] neg_lo:[0,1] neg_hi:[0,1]
	v_pk_add_f32 v[110:111], v[110:111], v[172:173] op_sel_hi:[1,0] neg_lo:[0,1] neg_hi:[0,1]
	v_pk_add_f32 v[96:97], v[96:97], v[172:173] op_sel_hi:[1,0] neg_lo:[0,1] neg_hi:[0,1]
	v_pk_add_f32 v[98:99], v[98:99], v[172:173] op_sel_hi:[1,0] neg_lo:[0,1] neg_hi:[0,1]
	v_pk_add_f32 v[100:101], v[100:101], v[172:173] op_sel_hi:[1,0] neg_lo:[0,1] neg_hi:[0,1]
	v_pk_add_f32 v[104:105], v[104:105], v[172:173] op_sel_hi:[1,0] neg_lo:[0,1] neg_hi:[0,1]
	v_pk_add_f32 v[106:107], v[106:107], v[172:173] op_sel_hi:[1,0] neg_lo:[0,1] neg_hi:[0,1]
	v_pk_add_f32 v[108:109], v[108:109], v[172:173] op_sel_hi:[1,0] neg_lo:[0,1] neg_hi:[0,1]
	v_pk_add_f32 v[94:95], v[94:95], v[172:173] op_sel_hi:[1,0] neg_lo:[0,1] neg_hi:[0,1]
	v_max_f32_e32 v50, v102, v103
	v_max_f32_e32 v53, v110, v111
	v_pk_add_f32 v[82:83], v[82:83], v[172:173] op_sel_hi:[1,0] neg_lo:[0,1] neg_hi:[0,1]
	v_pk_add_f32 v[86:87], v[86:87], v[172:173] op_sel_hi:[1,0] neg_lo:[0,1] neg_hi:[0,1]
	v_pk_add_f32 v[88:89], v[88:89], v[172:173] op_sel_hi:[1,0] neg_lo:[0,1] neg_hi:[0,1]
	v_pk_add_f32 v[90:91], v[90:91], v[172:173] op_sel_hi:[1,0] neg_lo:[0,1] neg_hi:[0,1]
	v_pk_add_f32 v[92:93], v[92:93], v[172:173] op_sel_hi:[1,0] neg_lo:[0,1] neg_hi:[0,1]
	v_max_f32_e32 v48, v96, v97
	v_max_f32_e32 v49, v98, v99
	v_max3_f32 v50, v100, v101, v50
	v_max_f32_e32 v51, v104, v105
	v_max_f32_e32 v52, v106, v107
	v_max3_f32 v53, v108, v109, v53
	v_max_f32_e32 v54, v94, v95
	v_pk_add_f32 v[80:81], v[80:81], v[172:173] op_sel_hi:[1,0] neg_lo:[0,1] neg_hi:[0,1]
	v_pk_add_f32 v[84:85], v[84:85], v[172:173] op_sel_hi:[1,0] neg_lo:[0,1] neg_hi:[0,1]
	v_max3_f32 v48, v48, v49, v50
	v_max3_f32 v49, v51, v52, v53
	v_max_f32_e32 v50, v82, v83
	v_max_f32_e32 v51, v86, v87
	v_max_f32_e32 v52, v88, v89
	v_max_f32_e32 v53, v90, v91
	v_max3_f32 v54, v92, v93, v54
	v_max3_f32 v50, v80, v81, v50
	v_max3_f32 v51, v84, v85, v51
	v_max3_f32 v52, v52, v53, v54
	v_max3_f32 v50, v50, v51, v52
	v_max3_f32 v48, v48, v49, v50
	ds_bpermute_b32 v49, v218, v48
	s_mov_b32 s8, 0x41000000
	s_waitcnt lgkmcnt(0)
	v_max_f32_e32 v49, v49, v49
	v_max_f32_e32 v48, v48, v49
	v_cmp_lt_f32_e32 vcc, s8, v48
	s_cbranch_vccz .LBB0_1216
	v_max_f32_e32 v48, v48, v48
	v_max_f32_e32 v49, 0, v48
	v_exp_f32_e64 v48, -v49
	v_sub_f32_e32 v96, v96, v49
	v_sub_f32_e32 v97, v97, v49
	v_sub_f32_e32 v98, v98, v49
	v_sub_f32_e32 v99, v99, v49
	v_sub_f32_e32 v100, v100, v49
	v_sub_f32_e32 v101, v101, v49
	v_sub_f32_e32 v102, v102, v49
	v_sub_f32_e32 v103, v103, v49
	v_sub_f32_e32 v104, v104, v49
	v_sub_f32_e32 v105, v105, v49
	v_sub_f32_e32 v106, v106, v49
	v_sub_f32_e32 v107, v107, v49
	v_sub_f32_e32 v108, v108, v49
	v_sub_f32_e32 v109, v109, v49
	v_sub_f32_e32 v110, v110, v49
	v_sub_f32_e32 v111, v111, v49
	v_sub_f32_e32 v80, v80, v49
	v_sub_f32_e32 v81, v81, v49
	v_sub_f32_e32 v82, v82, v49
	v_sub_f32_e32 v83, v83, v49
	v_sub_f32_e32 v84, v84, v49
	v_sub_f32_e32 v85, v85, v49
	v_sub_f32_e32 v86, v86, v49
	v_sub_f32_e32 v87, v87, v49
	v_sub_f32_e32 v88, v88, v49
	v_sub_f32_e32 v89, v89, v49
	v_sub_f32_e32 v90, v90, v49
	v_sub_f32_e32 v91, v91, v49
	v_sub_f32_e32 v92, v92, v49
	v_sub_f32_e32 v93, v93, v49
	v_sub_f32_e32 v94, v94, v49
	v_sub_f32_e32 v95, v95, v49
	v_pk_mul_f32 v[14:15], v[14:15], v[48:49] op_sel_hi:[1,0]
	v_pk_mul_f32 v[12:13], v[12:13], v[48:49] op_sel_hi:[1,0]
	v_pk_mul_f32 v[10:11], v[10:11], v[48:49] op_sel_hi:[1,0]
	v_pk_mul_f32 v[8:9], v[8:9], v[48:49] op_sel_hi:[1,0]
	v_pk_mul_f32 v[6:7], v[6:7], v[48:49] op_sel_hi:[1,0]
	v_pk_mul_f32 v[4:5], v[4:5], v[48:49] op_sel_hi:[1,0]
	v_pk_mul_f32 v[2:3], v[2:3], v[48:49] op_sel_hi:[1,0]
	v_pk_mul_f32 v[0:1], v[0:1], v[48:49] op_sel_hi:[1,0]
	v_pk_mul_f32 v[30:31], v[30:31], v[48:49] op_sel_hi:[1,0]
	v_pk_mul_f32 v[28:29], v[28:29], v[48:49] op_sel_hi:[1,0]
	v_pk_mul_f32 v[26:27], v[26:27], v[48:49] op_sel_hi:[1,0]
	v_pk_mul_f32 v[24:25], v[24:25], v[48:49] op_sel_hi:[1,0]
	v_pk_mul_f32 v[22:23], v[22:23], v[48:49] op_sel_hi:[1,0]
	v_pk_mul_f32 v[20:21], v[20:21], v[48:49] op_sel_hi:[1,0]
	v_pk_mul_f32 v[18:19], v[18:19], v[48:49] op_sel_hi:[1,0]
	v_pk_mul_f32 v[16:17], v[16:17], v[48:49] op_sel_hi:[1,0]
	v_pk_mul_f32 v[46:47], v[46:47], v[48:49] op_sel_hi:[1,0]
	v_pk_mul_f32 v[44:45], v[44:45], v[48:49] op_sel_hi:[1,0]
	v_pk_mul_f32 v[42:43], v[42:43], v[48:49] op_sel_hi:[1,0]
	v_pk_mul_f32 v[40:41], v[40:41], v[48:49] op_sel_hi:[1,0]
	v_pk_mul_f32 v[38:39], v[38:39], v[48:49] op_sel_hi:[1,0]
	v_pk_mul_f32 v[36:37], v[36:37], v[48:49] op_sel_hi:[1,0]
	v_pk_mul_f32 v[34:35], v[34:35], v[48:49] op_sel_hi:[1,0]
	v_pk_mul_f32 v[32:33], v[32:33], v[48:49] op_sel_hi:[1,0]
	v_add_f32_e32 v172, v172, v49
	s_branch .LBB0_1216
.Lmla_nf_4:
	v_pk_add_f32 v[70:71], v[70:71], v[172:173] op_sel_hi:[1,0] neg_lo:[0,1] neg_hi:[0,1]
	v_pk_add_f32 v[78:79], v[78:79], v[172:173] op_sel_hi:[1,0] neg_lo:[0,1] neg_hi:[0,1]
	v_pk_add_f32 v[64:65], v[64:65], v[172:173] op_sel_hi:[1,0] neg_lo:[0,1] neg_hi:[0,1]
	v_pk_add_f32 v[66:67], v[66:67], v[172:173] op_sel_hi:[1,0] neg_lo:[0,1] neg_hi:[0,1]
	v_pk_add_f32 v[68:69], v[68:69], v[172:173] op_sel_hi:[1,0] neg_lo:[0,1] neg_hi:[0,1]
	v_pk_add_f32 v[72:73], v[72:73], v[172:173] op_sel_hi:[1,0] neg_lo:[0,1] neg_hi:[0,1]
	v_pk_add_f32 v[74:75], v[74:75], v[172:173] op_sel_hi:[1,0] neg_lo:[0,1] neg_hi:[0,1]
	v_pk_add_f32 v[76:77], v[76:77], v[172:173] op_sel_hi:[1,0] neg_lo:[0,1] neg_hi:[0,1]
	v_pk_add_f32 v[62:63], v[62:63], v[172:173] op_sel_hi:[1,0] neg_lo:[0,1] neg_hi:[0,1]
	v_max_f32_e32 v82, v70, v71
	v_max_f32_e32 v85, v78, v79
	v_pk_add_f32 v[50:51], v[50:51], v[172:173] op_sel_hi:[1,0] neg_lo:[0,1] neg_hi:[0,1]
	v_pk_add_f32 v[54:55], v[54:55], v[172:173] op_sel_hi:[1,0] neg_lo:[0,1] neg_hi:[0,1]
	v_pk_add_f32 v[56:57], v[56:57], v[172:173] op_sel_hi:[1,0] neg_lo:[0,1] neg_hi:[0,1]
	v_pk_add_f32 v[58:59], v[58:59], v[172:173] op_sel_hi:[1,0] neg_lo:[0,1] neg_hi:[0,1]
	v_pk_add_f32 v[60:61], v[60:61], v[172:173] op_sel_hi:[1,0] neg_lo:[0,1] neg_hi:[0,1]
	v_max_f32_e32 v80, v64, v65
	v_max_f32_e32 v81, v66, v67
	v_max3_f32 v82, v68, v69, v82
	v_max_f32_e32 v83, v72, v73
	v_max_f32_e32 v84, v74, v75
	v_max3_f32 v85, v76, v77, v85
	v_max_f32_e32 v86, v62, v63
	v_pk_add_f32 v[48:49], v[48:49], v[172:173] op_sel_hi:[1,0] neg_lo:[0,1] neg_hi:[0,1]
	v_pk_add_f32 v[52:53], v[52:53], v[172:173] op_sel_hi:[1,0] neg_lo:[0,1] neg_hi:[0,1]
	v_max3_f32 v80, v80, v81, v82
	v_max3_f32 v81, v83, v84, v85
	v_max_f32_e32 v82, v50, v51
	v_max_f32_e32 v83, v54, v55
	v_max_f32_e32 v84, v56, v57
	v_max_f32_e32 v85, v58, v59
	v_max3_f32 v86, v60, v61, v86
	v_max3_f32 v82, v48, v49, v82
	v_max3_f32 v83, v52, v53, v83
	v_max3_f32 v84, v84, v85, v86
	v_max3_f32 v82, v82, v83, v84
	v_max3_f32 v80, v80, v81, v82
	ds_bpermute_b32 v81, v218, v80
	s_mov_b32 s8, 0x41000000
	s_waitcnt lgkmcnt(0)
	v_max_f32_e32 v81, v81, v81
	v_max_f32_e32 v80, v80, v81
	v_cmp_lt_f32_e32 vcc, s8, v80
	s_cbranch_vccz .LBB0_1219
	v_max_f32_e32 v80, v80, v80
	v_max_f32_e32 v81, 0, v80
	v_exp_f32_e64 v80, -v81
	v_sub_f32_e32 v64, v64, v81
	v_sub_f32_e32 v65, v65, v81
	v_sub_f32_e32 v66, v66, v81
	v_sub_f32_e32 v67, v67, v81
	v_sub_f32_e32 v68, v68, v81
	v_sub_f32_e32 v69, v69, v81
	v_sub_f32_e32 v70, v70, v81
	v_sub_f32_e32 v71, v71, v81
	v_sub_f32_e32 v72, v72, v81
	v_sub_f32_e32 v73, v73, v81
	v_sub_f32_e32 v74, v74, v81
	v_sub_f32_e32 v75, v75, v81
	v_sub_f32_e32 v76, v76, v81
	v_sub_f32_e32 v77, v77, v81
	v_sub_f32_e32 v78, v78, v81
	v_sub_f32_e32 v79, v79, v81
	v_sub_f32_e32 v48, v48, v81
	v_sub_f32_e32 v49, v49, v81
	v_sub_f32_e32 v50, v50, v81
	v_sub_f32_e32 v51, v51, v81
	v_sub_f32_e32 v52, v52, v81
	v_sub_f32_e32 v53, v53, v81
	v_sub_f32_e32 v54, v54, v81
	v_sub_f32_e32 v55, v55, v81
	v_sub_f32_e32 v56, v56, v81
	v_sub_f32_e32 v57, v57, v81
	v_sub_f32_e32 v58, v58, v81
	v_sub_f32_e32 v59, v59, v81
	v_sub_f32_e32 v60, v60, v81
	v_sub_f32_e32 v61, v61, v81
	v_sub_f32_e32 v62, v62, v81
	v_sub_f32_e32 v63, v63, v81
	v_pk_mul_f32 v[14:15], v[14:15], v[80:81] op_sel_hi:[1,0]
	v_pk_mul_f32 v[12:13], v[12:13], v[80:81] op_sel_hi:[1,0]
	v_pk_mul_f32 v[10:11], v[10:11], v[80:81] op_sel_hi:[1,0]
	v_pk_mul_f32 v[8:9], v[8:9], v[80:81] op_sel_hi:[1,0]
	v_pk_mul_f32 v[6:7], v[6:7], v[80:81] op_sel_hi:[1,0]
	v_pk_mul_f32 v[4:5], v[4:5], v[80:81] op_sel_hi:[1,0]
	v_pk_mul_f32 v[2:3], v[2:3], v[80:81] op_sel_hi:[1,0]
	v_pk_mul_f32 v[0:1], v[0:1], v[80:81] op_sel_hi:[1,0]
	v_pk_mul_f32 v[30:31], v[30:31], v[80:81] op_sel_hi:[1,0]
	v_pk_mul_f32 v[28:29], v[28:29], v[80:81] op_sel_hi:[1,0]
	v_pk_mul_f32 v[26:27], v[26:27], v[80:81] op_sel_hi:[1,0]
	v_pk_mul_f32 v[24:25], v[24:25], v[80:81] op_sel_hi:[1,0]
	v_pk_mul_f32 v[22:23], v[22:23], v[80:81] op_sel_hi:[1,0]
	v_pk_mul_f32 v[20:21], v[20:21], v[80:81] op_sel_hi:[1,0]
	v_pk_mul_f32 v[18:19], v[18:19], v[80:81] op_sel_hi:[1,0]
	v_pk_mul_f32 v[16:17], v[16:17], v[80:81] op_sel_hi:[1,0]
	v_pk_mul_f32 v[46:47], v[46:47], v[80:81] op_sel_hi:[1,0]
	v_pk_mul_f32 v[44:45], v[44:45], v[80:81] op_sel_hi:[1,0]
	v_pk_mul_f32 v[42:43], v[42:43], v[80:81] op_sel_hi:[1,0]
	v_pk_mul_f32 v[40:41], v[40:41], v[80:81] op_sel_hi:[1,0]
	v_pk_mul_f32 v[38:39], v[38:39], v[80:81] op_sel_hi:[1,0]
	v_pk_mul_f32 v[36:37], v[36:37], v[80:81] op_sel_hi:[1,0]
	v_pk_mul_f32 v[34:35], v[34:35], v[80:81] op_sel_hi:[1,0]
	v_pk_mul_f32 v[32:33], v[32:33], v[80:81] op_sel_hi:[1,0]
	v_add_f32_e32 v172, v172, v81
	s_branch .LBB0_1219
